# static s_setprio 2 for waves 0-3 inside the mLSTM chunk loop (they are the critical half), on top of the previous version
# baseline (speedup 1.0000x reference)
; template <int SKIP>
; DEV void mlstm_phase(LAS char* shm, const bf16_t* q, const bf16_t* k, const bf16_t* v, const float* gpart, const float* b_ig, const float* b_fg, bf16_t* hc, const bool pre) {
;     ...
;     for (int item = blockIdx.x; item < BATCH * NH * 8; item += gridDim.x) {
;     ...
;         asm volatile("s_waitcnt vmcnt(0)" ::: "memory");
.LBB0_593:
	s_setprio 0
	s_waitcnt vmcnt(0)
	s_add_i32 s79, s79, s3
	s_add_i32 s78, s78, s72
	s_cmpk_gt_i32 s79, 0xff
	s_cbranch_scc1 .LBB0_676

; #define LAS __attribute__((address_space(3)))
; template <int SKIP>
; DEV void mlstm_phase(LAS char* shm, const bf16_t* q, const bf16_t* k, const bf16_t* v, const float* gpart, const float* b_ig, const float* b_fg, bf16_t* hc, const bool pre) {
;     ...
;         for (int j = 0; j < SEQ / CHUNK; ++j) {
;             const size_t cb = cb0 + (size_t)j * CHUNK * DM;
;             const float btot = __int_as_float(__builtin_amdgcn_readfirstlane(__float_as_int(tc[2 * j]))), amax = __int_as_float(__builtin_amdgcn_readfirstlane(__float_as_int(tc[2 * j + 1])));
;             const float mxc = __int_as_float(__builtin_amdgcn_readfirstlane(__float_as_int(fmaxf(m_prev, amax))));
;             const LAS char* kbuf = shm + ((j & 1) << 15);
;             if (wid < 4) asm volatile("s_waitcnt vmcnt(1)" ::: "memory");
.LBB0_634:
	s_cmp_lt_u32 s61, 4
	s_cbranch_scc0 .Lpr0_skip
	s_setprio 2

; template <int SKIP>
; DEV void mlstm_phase(LAS char* shm, const bf16_t* q, const bf16_t* k, const bf16_t* v, const float* gpart, const float* b_ig, const float* b_fg, bf16_t* hc, const bool pre) {
;     ...
;     for (int item = blockIdx.x; item < BATCH * NH * 8; item += gridDim.x) {
;     ...
;         asm volatile("s_waitcnt vmcnt(0)" ::: "memory");
.LBB0_1445:
	s_setprio 0
	s_waitcnt vmcnt(0)
	s_add_i32 s91, s91, s3
	s_add_i32 s79, s79, s80
	s_cmpk_gt_i32 s91, 0xff
	s_cbranch_scc1 .LBB0_1527

; #define LAS __attribute__((address_space(3)))
; template <int SKIP>
; DEV void mlstm_phase(LAS char* shm, const bf16_t* q, const bf16_t* k, const bf16_t* v, const float* gpart, const float* b_ig, const float* b_fg, bf16_t* hc, const bool pre) {
;     ...
;         for (int j = 0; j < SEQ / CHUNK; ++j) {
;             const size_t cb = cb0 + (size_t)j * CHUNK * DM;
;             const float btot = __int_as_float(__builtin_amdgcn_readfirstlane(__float_as_int(tc[2 * j]))), amax = __int_as_float(__builtin_amdgcn_readfirstlane(__float_as_int(tc[2 * j + 1])));
;             const float mxc = __int_as_float(__builtin_amdgcn_readfirstlane(__float_as_int(fmaxf(m_prev, amax))));
;             const LAS char* kbuf = shm + ((j & 1) << 15);
;             if (wid < 4) asm volatile("s_waitcnt vmcnt(1)" ::: "memory");
.LBB0_1485:
	s_cmp_lt_u32 s47, 4
	s_cbranch_scc0 .Lpr1_skip
	s_setprio 2
